# older half (waves 0-3) at priority 1 through the compressed / top-k / window parts of the attention items; younger half still at priority 2 inside the selected-attention loop and ssd_s3
# speedup vs baseline: 1.0128x; 1.0128x over previous
.LBB0_1254:
	s_andn2_b64 vcc, exec, s[6:7]
	s_cbranch_vccnz .LBB0_2256
	s_mov_b64 s[4:5], s[0:1]
	s_load_dwordx2 s[90:91], s[4:5], 0xd8
	v_readfirstlane_b32 s2, v180
	s_ashr_i32 s2, s2, 6
	s_cmp_lt_u32 s2, 4
	s_cbranch_scc0 .Latt_prio_skip
	s_setprio 1

.Lbm2_done:
	v_readfirstlane_b32 s83, v1
	s_bitcmp1_b32 s83, 8
	s_cbranch_scc0 .Lbm2_pr0skip
	s_setprio 0
